# FFN-out decode-row (skinny) task: all 44 operand loads issued together in first-use order, MFMAs in original order behind counted waits
# speedup vs baseline: 1.0145x; 1.0025x over previous
; #define LAS __attribute__((address_space(3)))
; template <class Epi>
; DI void skinny_task(LAS unsigned char* lds, const bf16_t* A, int lda, const bf16_t* Bt, int K, int n0, const Epi& E, int wave, int lane) {
;     ...
; #pragma unroll 2
;     for (int k = 0; k < ksl; k += 32) {
;         const bf16x8 a0 = *(const bf16x8*)(ap + k), a1 = *(const bf16x8*)(ap + (size_t)16 * lda + k);
;         const bf16x8 b0 = *(const bf16x8*)(bp + k), b1 = *(const bf16x8*)(bp + (size_t)4 * K + k);
;         acc[0][0] = __builtin_amdgcn_mfma_f32_16x16x32_bf16(b0, a0, acc[0][0], 0, 0, 0); acc[0][1] = __builtin_amdgcn_mfma_f32_16x16x32_bf16(b1, a0, acc[0][1], 0, 0, 0);
;         acc[1][0] = __builtin_amdgcn_mfma_f32_16x16x32_bf16(b0, a1, acc[1][0], 0, 0, 0); acc[1][1] = __builtin_amdgcn_mfma_f32_16x16x32_bf16(b1, a1, acc[1][1], 0, 0, 0);
;     }
;     LAS float* P = (LAS float*)lds;
;     __syncthreads();
.LBB0_2410:
	v_add_u32_e32 v37, s6, v34
	v_mad_i64_i32 v[90:91], s[2:3], v37, s8, v[4:5]
	v_add_co_u32_e32 v92, vcc, 0x5000, v90
	s_nop 1
	v_addc_co_u32_e32 v93, vcc, 0, v91, vcc
	global_load_dwordx4 v[56:59], v[90:91], off
	global_load_dwordx4 v[60:63], v[2:3], off
	global_load_dwordx4 v[64:67], v[6:7], off
	global_load_dwordx4 v[68:71], v[92:93], off offset:2048
	global_load_dwordx4 v[72:75], v[2:3], off offset:64
	global_load_dwordx4 v[76:79], v[90:91], off offset:64
	global_load_dwordx4 v[80:83], v[14:15], off
	global_load_dwordx4 v[84:87], v[92:93], off offset:2112
	global_load_dwordx4 v[116:119], v[2:3], off offset:128
	global_load_dwordx4 v[120:123], v[92:93], off offset:2176
	global_load_dwordx4 v[124:127], v[16:17], off
	global_load_dwordx4 v[128:131], v[90:91], off offset:128
	global_load_dwordx4 v[132:135], v[90:91], off offset:192
	global_load_dwordx4 v[136:139], v[2:3], off offset:192
	global_load_dwordx4 v[140:143], v[18:19], off
	global_load_dwordx4 v[144:147], v[92:93], off offset:2240
	global_load_dwordx4 v[148:151], v[20:21], off
	global_load_dwordx4 v[152:155], v[90:91], off offset:256
	global_load_dwordx4 v[160:163], v[2:3], off offset:256
	global_load_dwordx4 v[164:167], v[92:93], off offset:2304
	global_load_dwordx4 v[168:171], v[90:91], off offset:320
	global_load_dwordx4 v[172:175], v[2:3], off offset:320
	global_load_dwordx4 v[176:179], v[22:23], off
	global_load_dwordx4 v[180:183], v[92:93], off offset:2368
	global_load_dwordx4 v[184:187], v[90:91], off offset:384
	global_load_dwordx4 v[188:191], v[2:3], off offset:384
	global_load_dwordx4 v[192:195], v[24:25], off
	global_load_dwordx4 v[196:199], v[92:93], off offset:2432
	global_load_dwordx4 v[200:203], v[90:91], off offset:448
	global_load_dwordx4 v[204:207], v[2:3], off offset:448
	global_load_dwordx4 v[208:211], v[92:93], off offset:2496
	global_load_dwordx4 v[212:215], v[26:27], off
	global_load_dwordx4 v[216:219], v[92:93], off offset:2560
	global_load_dwordx4 v[220:223], v[28:29], off
	global_load_dwordx4 v[224:227], v[2:3], off offset:512
	global_load_dwordx4 v[228:231], v[90:91], off offset:512
	global_load_dwordx4 v[232:235], v[2:3], off offset:576
	global_load_dwordx4 v[236:239], v[90:91], off offset:576
	global_load_dwordx4 v[240:243], v[92:93], off offset:2624
	global_load_dwordx4 v[244:247], v[30:31], off
	global_load_dwordx4 v[248:251], v[2:3], off offset:640
	s_waitcnt vmcnt(39)
	v_mfma_f32_16x16x32_bf16 v[40:43], v[56:59], v[60:63], 0
	s_waitcnt vmcnt(38)
	v_mfma_f32_16x16x32_bf16 v[44:47], v[56:59], v[64:67], 0
	s_waitcnt vmcnt(37)
	v_mfma_f32_16x16x32_bf16 v[48:51], v[68:71], v[60:63], 0
	s_waitcnt vmcnt(37)
	v_mfma_f32_16x16x32_bf16 v[52:55], v[68:71], v[64:67], 0
	global_load_dwordx4 v[56:59], v[90:91], off offset:640
	global_load_dwordx4 v[60:63], v[92:93], off offset:2688
	global_load_dwordx4 v[64:67], v[32:33], off
	s_waitcnt vmcnt(38)
	v_mfma_f32_16x16x32_bf16 v[40:43], v[76:79], v[72:75], v[40:43]
	s_waitcnt vmcnt(37)
	v_mfma_f32_16x16x32_bf16 v[44:47], v[76:79], v[80:83], v[44:47]
	s_waitcnt vmcnt(36)
	v_mfma_f32_16x16x32_bf16 v[48:51], v[84:87], v[72:75], v[48:51]
	s_waitcnt vmcnt(36)
	v_mfma_f32_16x16x32_bf16 v[52:55], v[84:87], v[80:83], v[52:55]
	s_waitcnt vmcnt(34)
	v_mfma_f32_16x16x32_bf16 v[48:51], v[120:123], v[116:119], v[48:51]
	s_waitcnt vmcnt(33)
	v_mfma_f32_16x16x32_bf16 v[52:55], v[120:123], v[124:127], v[52:55]
	s_waitcnt vmcnt(32)
	v_mfma_f32_16x16x32_bf16 v[40:43], v[128:131], v[116:119], v[40:43]
	s_waitcnt vmcnt(32)
	v_mfma_f32_16x16x32_bf16 v[44:47], v[128:131], v[124:127], v[44:47]
	s_waitcnt vmcnt(30)
	v_mfma_f32_16x16x32_bf16 v[40:43], v[132:135], v[136:139], v[40:43]
	s_waitcnt vmcnt(29)
	v_mfma_f32_16x16x32_bf16 v[44:47], v[132:135], v[140:143], v[44:47]
	s_waitcnt vmcnt(28)
	v_mfma_f32_16x16x32_bf16 v[48:51], v[144:147], v[136:139], v[48:51]
	s_waitcnt vmcnt(28)
	v_mfma_f32_16x16x32_bf16 v[52:55], v[144:147], v[140:143], v[52:55]
	s_waitcnt vmcnt(26)
	v_mfma_f32_16x16x32_bf16 v[44:47], v[152:155], v[148:151], v[44:47]
	s_waitcnt vmcnt(25)
	v_mfma_f32_16x16x32_bf16 v[40:43], v[152:155], v[160:163], v[40:43]
	s_waitcnt vmcnt(24)
	v_mfma_f32_16x16x32_bf16 v[48:51], v[164:167], v[160:163], v[48:51]
	s_waitcnt vmcnt(24)
	v_mfma_f32_16x16x32_bf16 v[52:55], v[164:167], v[148:151], v[52:55]
	s_waitcnt vmcnt(22)
	v_mfma_f32_16x16x32_bf16 v[40:43], v[168:171], v[172:175], v[40:43]
	s_waitcnt vmcnt(21)
	v_mfma_f32_16x16x32_bf16 v[44:47], v[168:171], v[176:179], v[44:47]
	s_waitcnt vmcnt(20)
	v_mfma_f32_16x16x32_bf16 v[48:51], v[180:183], v[172:175], v[48:51]
	s_waitcnt vmcnt(20)
	v_mfma_f32_16x16x32_bf16 v[52:55], v[180:183], v[176:179], v[52:55]
	s_waitcnt vmcnt(18)
	v_mfma_f32_16x16x32_bf16 v[40:43], v[184:187], v[188:191], v[40:43]
	s_waitcnt vmcnt(17)
	v_mfma_f32_16x16x32_bf16 v[44:47], v[184:187], v[192:195], v[44:47]
	s_waitcnt vmcnt(16)
	v_mfma_f32_16x16x32_bf16 v[48:51], v[196:199], v[188:191], v[48:51]
	s_waitcnt vmcnt(16)
	v_mfma_f32_16x16x32_bf16 v[52:55], v[196:199], v[192:195], v[52:55]
	s_waitcnt vmcnt(14)
	v_mfma_f32_16x16x32_bf16 v[40:43], v[200:203], v[204:207], v[40:43]
	s_waitcnt vmcnt(13)
	v_mfma_f32_16x16x32_bf16 v[48:51], v[208:211], v[204:207], v[48:51]
	s_waitcnt vmcnt(12)
	v_mfma_f32_16x16x32_bf16 v[44:47], v[200:203], v[212:215], v[44:47]
	s_waitcnt vmcnt(12)
	v_mfma_f32_16x16x32_bf16 v[52:55], v[208:211], v[212:215], v[52:55]
	s_waitcnt vmcnt(10)
	v_mfma_f32_16x16x32_bf16 v[52:55], v[216:219], v[220:223], v[52:55]
	s_waitcnt vmcnt(9)
	v_mfma_f32_16x16x32_bf16 v[48:51], v[216:219], v[224:227], v[48:51]
	s_waitcnt vmcnt(8)
	v_mfma_f32_16x16x32_bf16 v[40:43], v[228:231], v[224:227], v[40:43]
	s_waitcnt vmcnt(8)
	v_mfma_f32_16x16x32_bf16 v[44:47], v[228:231], v[220:223], v[44:47]
	s_waitcnt vmcnt(6)
	v_mfma_f32_16x16x32_bf16 v[40:43], v[236:239], v[232:235], v[40:43]
	s_waitcnt vmcnt(5)
	v_mfma_f32_16x16x32_bf16 v[48:51], v[240:243], v[232:235], v[48:51]
	s_waitcnt vmcnt(4)
	v_mfma_f32_16x16x32_bf16 v[44:47], v[236:239], v[244:247], v[44:47]
	s_waitcnt vmcnt(4)
	v_mfma_f32_16x16x32_bf16 v[52:55], v[240:243], v[244:247], v[52:55]
	s_waitcnt vmcnt(2)
	v_mfma_f32_16x16x32_bf16 v[40:43], v[56:59], v[248:251], v[40:43]
	s_waitcnt vmcnt(1)
	v_mfma_f32_16x16x32_bf16 v[48:51], v[60:63], v[248:251], v[48:51]
	s_waitcnt vmcnt(0)
	v_mfma_f32_16x16x32_bf16 v[44:47], v[56:59], v[64:67], v[44:47]
	s_waitcnt vmcnt(0)
	v_mfma_f32_16x16x32_bf16 v[52:55], v[60:63], v[64:67], v[52:55]
	s_waitcnt lgkmcnt(0)
	s_barrier
; #define LAS __attribute__((address_space(3)))
; DI void st8bf(bf16_t* p, f32x4 v0, f32x4 v1) { u32x4 w; w.x = pk2(v0.x, v0.y); w.y = pk2(v0.z, v0.w); w.z = pk2(v1.x, v1.y); w.w = pk2(v1.z, v1.w); *(u32x4*)p = w; }
; DI f32x4 ld4bf(const bf16_t* p) { const u32x2 w = *(const u32x2*)p; f32x4 o; o.x = bf2f(w.x & 0xffffu); o.y = bf2f(w.x >> 16); o.z = bf2f(w.y & 0xffffu); o.w = bf2f(w.y >> 16); return o; }
;     DI void elem(int row, int col0, f32x4 v0, f32x4 v1) const { st8bf(H + (size_t)row * 512 + col0, v0, v1); }
;     DI void elem(int row, int col0, f32x4 v0, f32x4 v1) const {
;         if (row >= MREAL) return;
;         const int mrow = row < MPR ? (row >> 11) : 8 + (row - MPR);
;         const float* gp = mod + (size_t)mrow * 6144 + goff + col0;
;         f32x4 s0, s1;
;         if (xin) { s0 = ld4bf(xin + (size_t)row * D + col0); s1 = ld4bf(xin + (size_t)row * D + col0 + 4); }
;         else { const float* src = row < MPR ? xp + (size_t)row * D + col0 : xs + (size_t)(row - MPR) * D + col0; s0 = *(const f32x4*)src; s1 = *(const f32x4*)(src + 4); }
;         st8bf(XO + (size_t)row * D + col0, s0 + *(const f32x4*)gp * v0, s1 + *(const f32x4*)(gp + 4) * v1);
;     }
; template <class Epi>
; DI void skinny_task(LAS unsigned char* lds, const bf16_t* A, int lda, const bf16_t* Bt, int K, int n0, const Epi& E, int wave, int lane) {
;     ...
;     LAS float* P = (LAS float*)lds;
;     __syncthreads();
; #pragma unroll
;     for (int mt = 0; mt < 2; ++mt)
; #pragma unroll
;         for (int nt = 0; nt < 2; ++nt) *(LAS f32x4*)(P + (wave * 32 + 16 * mt + fr) * 32 + 8 * fq + 4 * nt) = acc[mt][nt];
;     __syncthreads();
;     const int tid = wave * 64 + lane;
;     if (tid < 128) { const int row = tid >> 2, cg = tid & 3;
;         f32x4 s[2][2];
; #pragma unroll
;         for (int hf = 0; hf < 2; ++hf) { s[hf][0] = (f32x4){0.f, 0.f, 0.f, 0.f}; s[hf][1] = s[hf][0];
; #pragma unroll
;             for (int w = 0; w < 4; ++w) { const LAS float* p = P + ((4 * hf + w) * 32 + row) * 32 + 8 * cg; s[hf][0] = s[hf][0] + *(const LAS f32x4*)p; s[hf][1] = s[hf][1] + *(const LAS f32x4*)(p + 4); } }
;         if constexpr (Epi::HAS_MID) E.elem2(MPR + row, n0 + 8 * cg, s[0][0], s[0][1], s[1][0], s[1][1]);
;         else E.elem(MPR + row, n0 + 8 * cg, s[0][0] + s[1][0], s[0][1] + s[1][1]); }
	s_nop 7
	s_nop 7
	ds_write_b128 v35, v[40:43]
	ds_write_b128 v35, v[48:51] offset:16
	ds_write_b128 v35, v[44:47] offset:2048
	ds_write_b128 v35, v[52:55] offset:2064
	s_waitcnt lgkmcnt(0)
	s_barrier
	s_and_saveexec_b64 s[2:3], s[0:1]
	s_cbranch_execz .LBB0_2409
	v_add_u32_e32 v42, s6, v1
	v_ashrrev_i32_e32 v43, 31, v42
	v_lshlrev_b64 v[114:115], 1, v[42:43]
	v_lshl_add_u64 v[38:39], v[10:11], 0, v[114:115]
	global_load_dwordx4 v[38:41], v[38:39], off
	v_lshl_add_u64 v[50:51], v[42:43], 2, v[8:9]
	global_load_dwordx4 v[42:45], v[50:51], off
	global_load_dwordx4 v[46:49], v[50:51], off offset:16
	ds_read_b128 v[50:53], v36
	ds_read_b128 v[54:57], v36 offset:16
	ds_read_b128 v[58:61], v36 offset:4096
	ds_read_b128 v[62:65], v36 offset:4112
	ds_read_b128 v[66:69], v36 offset:8192
	ds_read_b128 v[70:73], v36 offset:8208
	ds_read_b128 v[74:77], v36 offset:12288
	ds_read_b128 v[78:81], v36 offset:12304
	ds_read_b128 v[82:85], v36 offset:16384
	ds_read_b128 v[86:89], v36 offset:16400
	ds_read_b128 v[90:93], v36 offset:20480
	ds_read_b128 v[94:97], v36 offset:20496
	ds_read_b128 v[98:101], v36 offset:24576
	ds_read_b128 v[102:105], v36 offset:24592
	ds_read_b128 v[106:109], v36 offset:28672
	ds_read_b128 v[110:113], v36 offset:28688
	s_waitcnt lgkmcnt(14)
	v_pk_add_f32 v[52:53], v[52:53], 0 op_sel_hi:[1,0]
	v_pk_add_f32 v[50:51], v[50:51], 0 op_sel_hi:[1,0]
	v_pk_add_f32 v[56:57], v[56:57], 0 op_sel_hi:[1,0]
	v_pk_add_f32 v[54:55], v[54:55], 0 op_sel_hi:[1,0]
	s_waitcnt lgkmcnt(7)
	v_pk_add_f32 v[84:85], v[84:85], 0 op_sel_hi:[1,0]
	v_pk_add_f32 v[82:83], v[82:83], 0 op_sel_hi:[1,0]
	s_waitcnt lgkmcnt(6)
	v_pk_add_f32 v[88:89], v[88:89], 0 op_sel_hi:[1,0]
	v_pk_add_f32 v[86:87], v[86:87], 0 op_sel_hi:[1,0]
	v_pk_add_f32 v[52:53], v[52:53], v[60:61]
	v_pk_add_f32 v[50:51], v[50:51], v[58:59]
	v_pk_add_f32 v[56:57], v[56:57], v[64:65]
	v_pk_add_f32 v[54:55], v[54:55], v[62:63]
	s_waitcnt lgkmcnt(5)
	v_pk_add_f32 v[58:59], v[84:85], v[92:93]
	v_pk_add_f32 v[60:61], v[82:83], v[90:91]
	s_waitcnt lgkmcnt(4)
	v_pk_add_f32 v[62:63], v[88:89], v[96:97]
	v_pk_add_f32 v[64:65], v[86:87], v[94:95]
	v_pk_add_f32 v[52:53], v[52:53], v[68:69]
	v_pk_add_f32 v[50:51], v[50:51], v[66:67]
	v_pk_add_f32 v[56:57], v[56:57], v[72:73]
	v_pk_add_f32 v[54:55], v[54:55], v[70:71]
	s_waitcnt lgkmcnt(3)
	v_pk_add_f32 v[58:59], v[58:59], v[100:101]
	v_pk_add_f32 v[60:61], v[60:61], v[98:99]
	s_waitcnt lgkmcnt(2)
	v_pk_add_f32 v[62:63], v[62:63], v[104:105]
	v_pk_add_f32 v[64:65], v[64:65], v[102:103]
	v_pk_add_f32 v[52:53], v[52:53], v[76:77]
	v_pk_add_f32 v[50:51], v[50:51], v[74:75]
	v_pk_add_f32 v[56:57], v[56:57], v[80:81]
	v_pk_add_f32 v[54:55], v[54:55], v[78:79]
	s_waitcnt lgkmcnt(1)
	v_pk_add_f32 v[58:59], v[58:59], v[108:109]
	v_pk_add_f32 v[60:61], v[60:61], v[106:107]
	s_waitcnt lgkmcnt(0)
	v_pk_add_f32 v[62:63], v[62:63], v[112:113]
	v_pk_add_f32 v[64:65], v[64:65], v[110:111]
	v_pk_add_f32 v[52:53], v[52:53], v[58:59]
	v_pk_add_f32 v[50:51], v[50:51], v[60:61]
	v_pk_add_f32 v[56:57], v[56:57], v[62:63]
	v_pk_add_f32 v[54:55], v[54:55], v[64:65]
	v_lshl_add_u64 v[114:115], v[12:13], 0, v[114:115]
	s_waitcnt vmcnt(2)
	v_lshlrev_b32_e32 v58, 16, v38
	v_and_b32_e32 v59, 0xffff0000, v38
	v_lshlrev_b32_e32 v38, 16, v39
	v_and_b32_e32 v39, 0xffff0000, v39
	v_lshlrev_b32_e32 v60, 16, v40
	v_and_b32_e32 v61, 0xffff0000, v40
	v_lshlrev_b32_e32 v40, 16, v41
	v_and_b32_e32 v41, 0xffff0000, v41
	s_waitcnt vmcnt(1)
	v_pk_fma_f32 v[44:45], v[52:53], v[44:45], v[38:39]
	v_pk_fma_f32 v[38:39], v[50:51], v[42:43], v[58:59]
	s_waitcnt vmcnt(0)
	v_pk_fma_f32 v[42:43], v[56:57], v[48:49], v[40:41]
	v_pk_fma_f32 v[40:41], v[54:55], v[46:47], v[60:61]
	v_cvt_pk_bf16_f32 v38, v38, v39
	v_cvt_pk_bf16_f32 v39, v44, v45
	v_cvt_pk_bf16_f32 v40, v40, v41
	v_cvt_pk_bf16_f32 v41, v42, v43
	global_store_dwordx4 v[114:115], v[38:41], off
	s_branch .LBB0_2409
